# RG-LRU sweeps: gate-weight MFMA fragments held in registers per item, A-operand LDS reads batched
# baseline (speedup 1.0000x reference)
.LBB0_324:
	s_or_b64 exec, exec, s[0:1]
	s_ashr_i32 s0, s33, 4
	s_lshl_b32 s1, s0, 8
	s_ashr_i32 s6, s1, 31
	s_add_u32 s70, s1, 0x10000
	s_addc_u32 s71, s6, 0
	s_lshl_b32 s1, s5, 7
	v_mov_b32_e32 v34, v32
	v_mov_b32_e32 v35, v32
	v_or_b32_e32 v2, s8, v134
	v_add_u32_e32 v6, s1, v137
	v_mov_b32_e32 v33, v32
	v_mov_b64_e32 v[42:43], v[34:35]
	v_mov_b64_e32 v[38:39], v[34:35]
	v_cmp_gt_u32_e32 vcc, s85, v6
	v_lshlrev_b32_e32 v2, 1, v2
	v_mov_b64_e32 v[40:41], v[32:33]
	v_mov_b64_e32 v[36:37], v[32:33]
	s_waitcnt lgkmcnt(0)
	s_barrier
	ds_read_b128 v[220:223], v156 offset:34816
	ds_read_b128 v[224:227], v156 offset:35840
	ds_read_b128 v[228:231], v156 offset:36864
	ds_read_b128 v[232:235], v156 offset:37888
	ds_read_b128 v[236:239], v156 offset:43008
	ds_read_b128 v[240:243], v156 offset:44032
	ds_read_b128 v[244:247], v156 offset:45056
	ds_read_b128 v[248:251], v156 offset:46080
	s_waitcnt lgkmcnt(0)
	s_and_saveexec_b64 s[8:9], vcc
	s_cbranch_execz .LBB0_326
	v_or_b32_e32 v3, s70, v6
	v_mov_b64_e32 v[8:9], s[28:29]
	v_mad_u64_u32 v[8:9], s[6:7], v3, s24, v[8:9]
	v_mad_i32_i24 v9, s71, v161, v9
	v_mov_b32_e32 v3, v32
	v_lshl_add_u64 v[8:9], v[8:9], 0, v[2:3]
	global_load_dwordx4 v[36:39], v[8:9], off offset:1552
	global_load_dwordx4 v[40:43], v[8:9], off offset:1536

.LBB0_356:
	s_waitcnt lgkmcnt(0)
	s_barrier
	ds_read_b128 v[0:3], v155
	ds_read_b128 v[4:7], v155 offset:16
	ds_read_b128 v[116:119], v155 offset:64
	ds_read_b128 v[120:123], v155 offset:80
	ds_read_b128 v[124:127], v155 offset:128
	ds_read_b128 v[188:191], v155 offset:144
	ds_read_b128 v[200:203], v155 offset:192
	ds_read_b128 v[208:211], v155 offset:208
	ds_read_b32 v170, v162
	v_cndmask_b32_e64 v33, 0, 1, s[8:9]
	s_mov_b64 s[0:1], -1
	s_waitcnt lgkmcnt(7)
	v_cvt_pk_bf16_f32 v0, v0, v1
	v_cvt_pk_bf16_f32 v1, v2, v3
	v_cvt_pk_bf16_f32 v2, v4, v5
	v_cvt_pk_bf16_f32 v3, v6, v7
	v_cmp_ne_u32_e32 vcc, 0, v33
	s_waitcnt lgkmcnt(5)
	v_cvt_pk_bf16_f32 v116, v116, v117
	v_cvt_pk_bf16_f32 v117, v118, v119
	v_cvt_pk_bf16_f32 v118, v120, v121
	v_cvt_pk_bf16_f32 v119, v122, v123
	v_mfma_f32_32x32x16_bf16 v[16:31], v[0:3], v[220:223], 0
	v_mfma_f32_32x32x16_bf16 v[0:15], v[0:3], v[236:239], 0
	s_waitcnt lgkmcnt(3)
	v_cvt_pk_bf16_f32 v124, v124, v125
	v_cvt_pk_bf16_f32 v125, v126, v127
	v_cvt_pk_bf16_f32 v126, v188, v189
	v_cvt_pk_bf16_f32 v127, v190, v191
	v_mfma_f32_32x32x16_bf16 v[16:31], v[116:119], v[224:227], v[16:31]
	v_mfma_f32_32x32x16_bf16 v[0:15], v[116:119], v[240:243], v[0:15]
	s_waitcnt lgkmcnt(1)
	v_cvt_pk_bf16_f32 v200, v200, v201
	v_cvt_pk_bf16_f32 v201, v202, v203
	v_cvt_pk_bf16_f32 v202, v208, v209
	v_cvt_pk_bf16_f32 v203, v210, v211
	v_mfma_f32_32x32x16_bf16 v[16:31], v[124:127], v[228:231], v[16:31]
	v_mfma_f32_32x32x16_bf16 v[0:15], v[124:127], v[244:247], v[0:15]
	v_mfma_f32_32x32x16_bf16 v[16:31], v[200:203], v[232:235], v[16:31]
	v_mfma_f32_32x32x16_bf16 v[0:15], v[200:203], v[248:251], v[0:15]
	s_nop 1
	s_nop 8
	v_fmamk_f32 v16, v16, 0xbfb8aa3b, v107
	v_exp_f32_e32 v16, v16
	s_nop 0
	v_add_f32_e32 v16, 1.0, v16
	v_rcp_f32_e32 v16, v16
	s_nop 0
	v_mul_f32_e32 v169, v165, v16
	v_add_f32_e32 v131, v169, v169
	v_fmamk_f32 v16, v131, 0x3c088889, v157
	v_fmaak_f32 v16, v131, v16, 0x3e2aaaab
	v_fma_f32 v16, v131, v16, 0.5
	v_fma_f32 v16, v131, v16, 1.0
	v_mul_f32_e64 v180, v16, -v131
	s_cbranch_vccnz .LBB0_390
	s_andn2_b64 vcc, exec, s[0:1]
	s_cbranch_vccnz .LBB0_359

.LBB0_561:
	s_or_b64 exec, exec, s[8:9]
	s_ashr_i32 s8, s64, 4
	s_ashr_i32 s9, s8, 31
	v_lshl_add_u32 v6, s10, 7, v107
	s_lshl_b64 s[48:49], s[8:9], 12
	v_add_u32_e32 v8, -2, v6
	v_mov_b32_e32 v9, v32
	v_lshl_add_u64 v[8:9], s[48:49], 0, v[8:9]
	v_mov_b64_e32 v[10:11], s[28:29]
	v_or_b32_e32 v4, s11, v104
	v_mad_u64_u32 v[12:13], s[8:9], v8, s54, v[10:11]
	v_mad_i32_i24 v13, v9, s54, v13
	v_lshlrev_b32_e32 v8, 1, v4
	v_mov_b32_e32 v9, v32
	v_lshl_add_u64 v[12:13], v[12:13], 0, v[8:9]
	s_waitcnt lgkmcnt(0)
	s_barrier
	ds_read_b128 v[220:223], v146 offset:34816
	ds_read_b128 v[224:227], v146 offset:35840
	ds_read_b128 v[228:231], v146 offset:36864
	ds_read_b128 v[232:235], v146 offset:37888
	ds_read_b128 v[236:239], v146 offset:43008
	ds_read_b128 v[240:243], v146 offset:44032
	ds_read_b128 v[244:247], v146 offset:45056
	ds_read_b128 v[248:251], v146 offset:46080
	s_waitcnt lgkmcnt(0)
	global_load_dwordx4 v[36:39], v[12:13], off offset:1552
	global_load_dwordx4 v[40:43], v[12:13], off offset:1536
	v_add_u32_e32 v12, -1, v6
	v_mov_b32_e32 v13, v32
	v_lshl_add_u64 v[12:13], s[48:49], 0, v[12:13]
	v_mad_u64_u32 v[14:15], s[8:9], v12, s54, v[10:11]
	v_mad_i32_i24 v15, v13, s54, v15
	v_lshl_add_u64 v[12:13], v[14:15], 0, v[8:9]
	v_mov_b32_e32 v7, v32
	global_load_dwordx4 v[48:51], v[12:13], off offset:1552
	global_load_dwordx4 v[44:47], v[12:13], off offset:1536
	v_lshl_add_u64 v[12:13], s[48:49], 0, v[6:7]
	v_add_u32_e32 v6, 1, v6
	v_lshl_add_u64 v[6:7], s[48:49], 0, v[6:7]
	v_mad_u64_u32 v[14:15], s[8:9], v12, s54, v[10:11]
	v_mad_u64_u32 v[10:11], s[8:9], v6, s54, v[10:11]
	v_mad_i32_i24 v15, v13, s54, v15
	v_mad_i32_i24 v11, v7, s54, v11
	v_lshl_add_u64 v[12:13], v[14:15], 0, v[8:9]
	v_lshl_add_u64 v[6:7], v[10:11], 0, v[8:9]
	global_load_dwordx4 v[52:55], v[12:13], off offset:1552
	global_load_dwordx4 v[56:59], v[12:13], off offset:1536
	global_load_dwordx4 v[60:63], v[6:7], off offset:1552
	global_load_dwordx4 v[64:67], v[6:7], off offset:1536
	global_load_dwordx4 v[68:71], v[12:13], off offset:2576
	global_load_dwordx4 v[72:75], v[12:13], off offset:2560
	v_mul_f32_e32 v155, 0xc1000000, v3
	s_waitcnt vmcnt(11)
	v_mul_f32_e32 v81, 0xbfb8aa3b, v1
	s_cmp_eq_u32 s10, 0
	v_mul_f32_e32 v1, -2.0, v155
	v_readlane_b32 s52, v254, 7
	s_cselect_b64 s[8:9], -1, 0
	s_cmp_lg_u32 s10, 0
	v_cmp_le_f32_e64 s[10:11], s55, v1
	v_ashrrev_i32_e32 v1, 31, v0
	v_readlane_b32 s53, v254, 8
	s_waitcnt vmcnt(10)
	v_mul_f32_e32 v154, 0xbfb8aa3b, v2
	s_mov_b32 s65, 0
	s_cselect_b64 s[50:51], -1, 0
	v_lshl_add_u64 v[82:83], v[0:1], 2, s[52:53]
	v_mov_b32_e32 v85, s49
	v_or_b32_e32 v84, s48, v194
	v_lshl_add_u64 v[86:87], s[28:29], 0, v[8:9]
	s_mov_b32 s66, 14
	s_mov_b32 s67, 17
	v_lshlrev_b32_e32 v88, 1, v4
	s_branch .LBB0_564

.LBB0_574:
	s_waitcnt lgkmcnt(0)
	s_barrier
	ds_read_b128 v[0:3], v145
	ds_read_b128 v[4:7], v145 offset:16
	ds_read_b128 v[94:97], v145 offset:64
	ds_read_b128 v[98:101], v145 offset:80
	ds_read_b128 v[90:93], v145 offset:128
	ds_read_b128 v[164:167], v145 offset:144
	ds_read_b128 v[180:183], v145 offset:192
	ds_read_b128 v[184:187], v145 offset:208
	ds_read_b32 v174, v153
	v_cndmask_b32_e64 v33, 0, 1, s[10:11]
	s_mov_b64 s[52:53], -1
	v_add_u32_e32 v89, 0x1000, v153
	s_waitcnt lgkmcnt(7)
	v_cvt_pk_bf16_f32 v0, v0, v1
	v_cvt_pk_bf16_f32 v1, v2, v3
	v_cvt_pk_bf16_f32 v2, v4, v5
	v_cvt_pk_bf16_f32 v3, v6, v7
	v_cmp_ne_u32_e32 vcc, 0, v33
	v_add_u32_e32 v33, 0x1800, v153
	s_waitcnt lgkmcnt(5)
	v_cvt_pk_bf16_f32 v94, v94, v95
	v_cvt_pk_bf16_f32 v95, v96, v97
	v_cvt_pk_bf16_f32 v96, v98, v99
	v_cvt_pk_bf16_f32 v97, v100, v101
	v_mfma_f32_32x32x16_bf16 v[16:31], v[0:3], v[220:223], 0
	v_mfma_f32_32x32x16_bf16 v[0:15], v[0:3], v[236:239], 0
	s_waitcnt lgkmcnt(3)
	v_cvt_pk_bf16_f32 v90, v90, v91
	v_cvt_pk_bf16_f32 v91, v92, v93
	v_cvt_pk_bf16_f32 v92, v164, v165
	v_cvt_pk_bf16_f32 v93, v166, v167
	v_mfma_f32_32x32x16_bf16 v[16:31], v[94:97], v[224:227], v[16:31]
	v_mfma_f32_32x32x16_bf16 v[0:15], v[94:97], v[240:243], v[0:15]
	s_waitcnt lgkmcnt(1)
	v_cvt_pk_bf16_f32 v180, v180, v181
	v_cvt_pk_bf16_f32 v181, v182, v183
	v_cvt_pk_bf16_f32 v182, v184, v185
	v_cvt_pk_bf16_f32 v183, v186, v187
	v_mfma_f32_32x32x16_bf16 v[16:31], v[90:93], v[228:231], v[16:31]
	v_mfma_f32_32x32x16_bf16 v[0:15], v[90:93], v[244:247], v[0:15]
	v_mfma_f32_32x32x16_bf16 v[16:31], v[180:183], v[232:235], v[16:31]
	v_mfma_f32_32x32x16_bf16 v[0:15], v[180:183], v[248:251], v[0:15]
	v_add_u32_e32 v157, 0x800, v153
	v_add_u32_e32 v156, 0x1200, v153
	s_nop 8
	v_fmamk_f32 v16, v16, 0xbfb8aa3b, v81
	v_exp_f32_e32 v16, v16
	s_nop 0
	v_add_f32_e32 v16, 1.0, v16
	v_rcp_f32_e32 v16, v16
	s_nop 0
	v_mul_f32_e32 v173, v155, v16
	v_add_f32_e32 v179, v173, v173
	v_fmamk_f32 v16, v179, 0x3c088889, v147
	v_fmaak_f32 v16, v179, v16, 0x3e2aaaab
	v_fma_f32 v16, v179, v16, 0.5
	v_fma_f32 v16, v179, v16, 1.0
	v_mul_f32_e64 v176, v16, -v179
	s_cbranch_vccnz .LBB0_600
	s_andn2_b64 vcc, exec, s[52:53]
	s_cbranch_vccnz .LBB0_577
